# windowed attention loop: same lazy rebase (row-max chain removed, check on step row sums) on top of v48
# baseline (speedup 1.0000x reference)
; #define LAS __attribute__((address_space(3)))
; DI float opaque0() { float z; asm volatile("v_mov_b32 %0, 0" : "=v"(z)); return z; }
; template <bool MASKED> ...
;     ...
;     const int lrow = tid >> 3, lkc = tid & 7;
;     auto tile_off = [&](int i) -> size_t {
;         const int r0 = (i < nlat) ? (lat_row0 + 64 * i) : (ctx_row0 + 64 * (i - nlat));
;         return (size_t)(r0 + lrow) * ldkv + kvcol + lkc * 8;
;     };
;     lchar* const Kbase = lds; lchar* const Vbase = lds + 2 * KV_K;
;     constexpr int VB = 64 * VSTR;
;     const int koff = lrow * KSTR + lkc * 16, voff = lrow * VSTR + lkc * 16;
;     f32x16 o[2][2];
;     { const float z0 = opaque0();
; #pragma unroll
;       for (int q = 0; q < 2; ++q)
; #pragma unroll
;         for (int dt = 0; dt < 2; ++dt)
; #pragma unroll
;             for (int i = 0; i < 16; ++i) o[q][dt][i] = z0; }
;     float m_ref[2] = {0.f, 0.f}, lsum[2] = {0.f, 0.f};
;     const int qw0 = __builtin_amdgcn_readfirstlane(qpos0 + wave * 64);
;     u32x4 rk, rv;
;     {
;         const u32x4 k0 = *(const u32x4*)(Kb + tile_off(0)), v0 = *(const u32x4*)(Vb + tile_off(0));
;         rk = *(const u32x4*)(Kb + tile_off(1)); rv = *(const u32x4*)(Vb + tile_off(1));
;         *(LAS u32x4*)(Kbase + koff) = k0; *(LAS u32x4*)(Vbase + voff) = v0;
;     }
;     __syncthreads();
;     {
;         *(LAS u32x4*)(Kbase + KV_K + koff) = rk; *(LAS u32x4*)(Vbase + VB + voff) = rv;
;         rk = *(const u32x4*)(Kb + tile_off(2)); rv = *(const u32x4*)(Vb + tile_off(2));
;         attn2_step<true, MASKED>(o, m_ref, lsum, qf, Kbase, Vbase, lane, kpos0, qw0, m_init, l0);
;         __syncthreads();
;     }
;     for (int it = 1; it < ntiles; ++it) {
.LBB0_206:
	s_andn2_b64 vcc, exec, s[0:1]
	s_cbranch_vccnz .LBB0_173
	v_readlane_b32 s40, v252, 31
	v_readlane_b32 s0, v252, 47
	v_lshlrev_b32_e32 v65, 3, v114
	v_readlane_b32 s1, v252, 48
	s_add_u32 s0, s0, s40
	s_addc_u32 s1, s1, 0
	v_lshlrev_b32_e32 v66, 1, v65
	v_mov_b32_e32 v67, v129
	v_lshl_add_u64 v[186:187], s[0:1], 0, v[66:67]
	s_add_u32 s0, s38, s40
	v_add_u32_e32 v65, s96, v112
	s_addc_u32 s1, s39, 0
	v_add_u32_e32 v185, 0xffffff7f, v65
	v_add_u32_e32 v190, 0xffffff5f, v65
	v_add_u32_e32 v191, 0xffffff9f, v65
	v_lshrrev_b32_e32 v65, 2, v111
	v_lshl_add_u64 v[188:189], s[0:1], 0, v[66:67]
	v_and_b32_e32 v66, 16, v111
	v_and_or_b32 v65, v65, 3, v184
	v_mul_u32_u24_e32 v65, 0xc0, v65
	v_and_or_b32 v64, v64, 12, v66
	v_readfirstlane_b32 s0, v110
	v_writelane_b32 v254, s97, 55
	s_add_i32 s37, s23, 3
	v_mul_u32_u24_e32 v175, 0x90, v112
	v_mul_u32_u24_e32 v179, 0x90, v115
	s_add_i32 s70, s96, 0xffffffbf
	s_add_i32 s71, s96, 0x41
	v_lshl_or_b32 v192, v64, 1, v65
	s_add_i32 s96, s0, 64
	s_mov_b32 s97, -3
	v_readlane_b32 s41, v252, 32
	v_mov_b32_e32 v240, 0
	v_mov_b32_e32 v242, 0
	s_branch .LBB0_210

; DI float fast_exp2(float x) { return __builtin_amdgcn_exp2f(x); }
; template <bool FIRST, bool MASKED>
; DI void attn2_step(f32x16 (&o)[2][2], float (&m_ref)[2], float (&lsum)[2], const bf16x8 (&qf)[2][4], const lchar* Kl, const lchar* Vl, int lane, int kp0, int qw0, float m_init, float l0) {
;     ...
;     } else if (__builtin_amdgcn_ballot_w64(fmaxf(mx[0], mx[1]) > ATT_THR) != 0ull) {
; #pragma unroll
;         for (int q = 0; q < 2; ++q) {
;             const float delta = fmaxf(mx[q], 0.f), alpha = fast_exp2(-delta);
; #pragma unroll
;             for (int dt = 0; dt < 2; ++dt)
; #pragma unroll
;                 for (int i = 0; i < 16; ++i) o[q][dt][i] *= alpha;
;             lsum[q] *= alpha;
; #pragma unroll
;             for (int kt = 0; kt < 2; ++kt)
; #pragma unroll
;                 for (int i = 0; i < 16; ++i) sc[q][kt][i] -= delta;
;             m_ref[q] += delta;
;         }
;     }
.LBB0_216:
	s_nop 8
	s_mov_b32 s0, 0x43800000
	v_max_f32_e32 v195, v240, v242
	v_cmp_lt_f32_e32 vcc, s0, v195
	s_cbranch_vccz .LBB0_208
	s_nop 15
	v_log_f32_e32 v193, v240
	v_log_f32_e32 v194, v242
	v_mov_b32_e32 v240, 0
	v_mov_b32_e32 v242, 0
	v_mov_b32_e32 v195, v193
	v_mov_b32_e32 v196, v194
	s_nop 1
	v_permlane32_swap_b32_e32 v195, v193
	v_permlane32_swap_b32_e32 v196, v194
	s_nop 1
	v_max_f32_e32 v193, v193, v195
	v_max_f32_e32 v194, v194, v196
	v_max_f32_e32 v193, v193, v193
	v_max_f32_e32 v196, 0, v193
	v_max_f32_e32 v193, v194, v194
	v_max_f32_e32 v194, 0, v193
	v_exp_f32_e64 v208, -v196
	v_exp_f32_e64 v210, -v194
	v_pk_add_f32 v[96:97], v[96:97], v[194:195] op_sel_hi:[1,0] neg_lo:[0,1] neg_hi:[0,1]
	v_pk_add_f32 v[98:99], v[98:99], v[194:195] op_sel_hi:[1,0] neg_lo:[0,1] neg_hi:[0,1]
	v_pk_add_f32 v[100:101], v[100:101], v[194:195] op_sel_hi:[1,0] neg_lo:[0,1] neg_hi:[0,1]
	v_pk_mul_f32 v[30:31], v[30:31], v[210:211] op_sel_hi:[1,0]
	v_pk_mul_f32 v[28:29], v[28:29], v[210:211] op_sel_hi:[1,0]
	v_pk_mul_f32 v[26:27], v[26:27], v[210:211] op_sel_hi:[1,0]
	v_pk_mul_f32 v[24:25], v[24:25], v[210:211] op_sel_hi:[1,0]
	v_pk_mul_f32 v[22:23], v[22:23], v[210:211] op_sel_hi:[1,0]
	v_pk_mul_f32 v[20:21], v[20:21], v[210:211] op_sel_hi:[1,0]
	v_pk_mul_f32 v[18:19], v[18:19], v[210:211] op_sel_hi:[1,0]
	v_pk_mul_f32 v[16:17], v[16:17], v[210:211] op_sel_hi:[1,0]
	v_pk_mul_f32 v[14:15], v[14:15], v[210:211] op_sel_hi:[1,0]
	v_pk_mul_f32 v[12:13], v[12:13], v[210:211] op_sel_hi:[1,0]
	v_pk_mul_f32 v[10:11], v[10:11], v[210:211] op_sel_hi:[1,0]
	v_pk_mul_f32 v[8:9], v[8:9], v[210:211] op_sel_hi:[1,0]
	v_pk_mul_f32 v[6:7], v[6:7], v[210:211] op_sel_hi:[1,0]
	v_pk_mul_f32 v[4:5], v[4:5], v[210:211] op_sel_hi:[1,0]
	v_pk_mul_f32 v[2:3], v[2:3], v[210:211] op_sel_hi:[1,0]
	v_pk_mul_f32 v[0:1], v[0:1], v[210:211] op_sel_hi:[1,0]
	v_mov_b32_e32 v211, v208
	v_pk_add_f32 v[102:103], v[102:103], v[194:195] op_sel_hi:[1,0] neg_lo:[0,1] neg_hi:[0,1]
	v_pk_add_f32 v[104:105], v[104:105], v[194:195] op_sel_hi:[1,0] neg_lo:[0,1] neg_hi:[0,1]
	v_pk_add_f32 v[106:107], v[106:107], v[194:195] op_sel_hi:[1,0] neg_lo:[0,1] neg_hi:[0,1]
	v_pk_add_f32 v[108:109], v[108:109], v[194:195] op_sel_hi:[1,0] neg_lo:[0,1] neg_hi:[0,1]
	v_pk_add_f32 v[110:111], v[110:111], v[194:195] op_sel_hi:[1,0] neg_lo:[0,1] neg_hi:[0,1]
	v_pk_add_f32 v[64:65], v[64:65], v[194:195] op_sel_hi:[1,0] neg_lo:[0,1] neg_hi:[0,1]
	v_pk_add_f32 v[66:67], v[66:67], v[194:195] op_sel_hi:[1,0] neg_lo:[0,1] neg_hi:[0,1]
	v_pk_add_f32 v[68:69], v[68:69], v[194:195] op_sel_hi:[1,0] neg_lo:[0,1] neg_hi:[0,1]
	v_pk_add_f32 v[70:71], v[70:71], v[194:195] op_sel_hi:[1,0] neg_lo:[0,1] neg_hi:[0,1]
	v_pk_add_f32 v[72:73], v[72:73], v[194:195] op_sel_hi:[1,0] neg_lo:[0,1] neg_hi:[0,1]
	v_pk_add_f32 v[74:75], v[74:75], v[194:195] op_sel_hi:[1,0] neg_lo:[0,1] neg_hi:[0,1]
	v_pk_add_f32 v[76:77], v[76:77], v[194:195] op_sel_hi:[1,0] neg_lo:[0,1] neg_hi:[0,1]
	v_pk_add_f32 v[78:79], v[78:79], v[194:195] op_sel_hi:[1,0] neg_lo:[0,1] neg_hi:[0,1]
	v_mov_b32_e32 v195, v196
	v_pk_mul_f32 v[46:47], v[46:47], v[208:209] op_sel_hi:[1,0]
	v_pk_mul_f32 v[44:45], v[44:45], v[208:209] op_sel_hi:[1,0]
	v_pk_mul_f32 v[42:43], v[42:43], v[208:209] op_sel_hi:[1,0]
	v_pk_mul_f32 v[40:41], v[40:41], v[208:209] op_sel_hi:[1,0]
	v_pk_mul_f32 v[38:39], v[38:39], v[208:209] op_sel_hi:[1,0]
	v_pk_mul_f32 v[36:37], v[36:37], v[208:209] op_sel_hi:[1,0]
	v_pk_mul_f32 v[34:35], v[34:35], v[208:209] op_sel_hi:[1,0]
	v_pk_mul_f32 v[32:33], v[32:33], v[208:209] op_sel_hi:[1,0]
	v_pk_mul_f32 v[62:63], v[62:63], v[208:209] op_sel_hi:[1,0]
	v_pk_mul_f32 v[60:61], v[60:61], v[208:209] op_sel_hi:[1,0]
	v_pk_mul_f32 v[58:59], v[58:59], v[208:209] op_sel_hi:[1,0]
	v_pk_mul_f32 v[56:57], v[56:57], v[208:209] op_sel_hi:[1,0]
	v_pk_mul_f32 v[54:55], v[54:55], v[208:209] op_sel_hi:[1,0]
	v_pk_mul_f32 v[52:53], v[52:53], v[208:209] op_sel_hi:[1,0]
	v_pk_mul_f32 v[50:51], v[50:51], v[208:209] op_sel_hi:[1,0]
	v_pk_mul_f32 v[48:49], v[48:49], v[208:209] op_sel_hi:[1,0]
	v_pk_add_f32 v[112:113], v[112:113], v[196:197] op_sel_hi:[1,0] neg_lo:[0,1] neg_hi:[0,1]
	v_pk_add_f32 v[114:115], v[114:115], v[196:197] op_sel_hi:[1,0] neg_lo:[0,1] neg_hi:[0,1]
	v_pk_add_f32 v[116:117], v[116:117], v[196:197] op_sel_hi:[1,0] neg_lo:[0,1] neg_hi:[0,1]
	v_pk_add_f32 v[118:119], v[118:119], v[196:197] op_sel_hi:[1,0] neg_lo:[0,1] neg_hi:[0,1]
	v_pk_add_f32 v[120:121], v[120:121], v[196:197] op_sel_hi:[1,0] neg_lo:[0,1] neg_hi:[0,1]
	v_pk_add_f32 v[122:123], v[122:123], v[196:197] op_sel_hi:[1,0] neg_lo:[0,1] neg_hi:[0,1]
	v_pk_add_f32 v[124:125], v[124:125], v[196:197] op_sel_hi:[1,0] neg_lo:[0,1] neg_hi:[0,1]
	v_pk_add_f32 v[126:127], v[126:127], v[196:197] op_sel_hi:[1,0] neg_lo:[0,1] neg_hi:[0,1]
	v_pk_add_f32 v[80:81], v[80:81], v[196:197] op_sel_hi:[1,0] neg_lo:[0,1] neg_hi:[0,1]
	v_pk_add_f32 v[82:83], v[82:83], v[196:197] op_sel_hi:[1,0] neg_lo:[0,1] neg_hi:[0,1]
	v_pk_add_f32 v[84:85], v[84:85], v[196:197] op_sel_hi:[1,0] neg_lo:[0,1] neg_hi:[0,1]
	v_pk_add_f32 v[86:87], v[86:87], v[196:197] op_sel_hi:[1,0] neg_lo:[0,1] neg_hi:[0,1]
	v_pk_add_f32 v[88:89], v[88:89], v[196:197] op_sel_hi:[1,0] neg_lo:[0,1] neg_hi:[0,1]
	v_pk_add_f32 v[90:91], v[90:91], v[196:197] op_sel_hi:[1,0] neg_lo:[0,1] neg_hi:[0,1]
	v_pk_add_f32 v[92:93], v[92:93], v[196:197] op_sel_hi:[1,0] neg_lo:[0,1] neg_hi:[0,1]
	v_pk_add_f32 v[94:95], v[94:95], v[196:197] op_sel_hi:[1,0] neg_lo:[0,1] neg_hi:[0,1]
	v_pk_mul_f32 v[180:181], v[180:181], v[210:211]
	v_pk_add_f32 v[182:183], v[182:183], v[194:195]
	s_branch .LBB0_208
